# v19: next item's first K/V tiles are DMA'd into the ring during the last three tiles of the current item
# baseline (speedup 1.0000x reference)
; __device__ __forceinline__ int v_st(int k, int c) { const int kk = (k & ~0xC) | ((k & 4) << 1) | ((k & 8) >> 1); return ((kk >> 3) * 4 + (c >> 5)) * 512 + ((kk & 7) * 32 + (c & 31)) * 2; }
; __device__ __forceinline__ int v_rd_base(int lane) { return ((lane & 3) << 3) | (((lane >> 2) & 3) << 6) | (((lane >> 4) & 1) << 5) | (((lane >> 5) & 1) << 8); }
; #define SLOAD(i, k0) do { sr_[i].vs = *(const bf16x8*)(Kh + (size_t)((k0) + skey) * 2048 + 64 + sc8); \
;     sr_[i].ks = *(const bf16x8*)(Kh + (size_t)((k0) + skey) * 2048 + sc8); \
;     sr_[i].ps = *(const bf16x8*)(Kp + (size_t)((k0) + pkey) * 32 + pc8); } while (0)
; #define SWRITE(bb, i) do { *(bf16x8*)(V_lds + (bb) * AT_SHMV + vst) = sr_[i].vs; \
;     *(bf16x8*)(K_lds + (bb) * AT_SHMK + kst) = sr_[i].ks; \
;     *(bf16x8*)(K_lds + (bb) * AT_SHMK + pst) = sr_[i].ps; } while (0)
; __device__ void phase_attn(const Params& p, char* lds) {
;     ...
;   const int tid = threadIdx.x, wid = tid >> 6, lane = tid & 63, r32 = lane & 31, hi = lane >> 5;
;   char* V_lds = lds; char* K_lds = lds + AT_KOFF;
;   float* wsl = (float*)(lds + AT_WOFF) + wid * 64; float* li_l = wsl; float* al_l = wsl + 32;
;   const int skey = tid >> 3, sc8 = (tid & 7) * 8;
;   const int pkey = (tid & 255) >> 2, pc8 = (tid & 3) * 8;
;   const int vst = v_st(skey, sc8), kst = skey * AT_KROW + sc8 * 2, pst = pkey * AT_KROW + (64 + pc8) * 2;
;   const int vb0 = (int)(uintptr_t)V_lds + v_rd_base(lane);
;   const int nitems = NB * 16 * 32;
;   const int xcd = blockIdx.x & 7, slot = blockIdx.x >> 3, per = gridDim.x >> 3;
;   for (int it = slot; it < nitems / 8; it += per) {
;     const int pair = (it >> 5) * 8 + xcd, qblk = it & 31;
;     const int b = pair >> 4, h = pair & 15;
;     const size_t row0 = (size_t)b * TL;
;     const size_t qrow = row0 + qblk * 256 + wid * 32 + r32;
;     const bf16_t* Kh = KVg + row0 * 2048 + h * 128;
;     const bf16_t* Kp = KPg + row0 * 32;
;     ...
;     f32x16 pA0, pA1, pB0, pB1; float alA, alB; bf16x8 pa0, pa1, pa2, pa3;
;     constexpr int NT = TL / 64;
;     SLOAD(0, 0); asm volatile("s_waitcnt vmcnt(0)" ::: "memory"); SWRITE(0, 0); __syncthreads();
.LBB0_991:
	s_or_b64 exec, exec, s[4:5]
	s_cmpk_gt_u32 s3, 0xfff
	s_waitcnt vmcnt(7)
	v_and_b32_e32 v128, 56, v183
	v_lshlrev_b32_e32 v168, 11, v161
	s_barrier
	v_and_b32_e32 v175, 63, v178
	v_and_b32_e32 v183, 31, v178
	v_lshrrev_b32_e32 v228, 5, v175
	v_readfirstlane_b32 s14, v178
	v_lshrrev_b32_e32 v229, 3, v178
	v_and_b32_e32 v230, 7, v178
	s_lshr_b32 s14, s14, 6
	s_lshr_b32 s15, s14, 2
	s_and_b32 s43, s3, 7
	s_mov_b32 s23, 0x453a4f54
	v_lshlrev_b32_e32 v129, 4, v230
	v_lshl_or_b32 v129, v229, 12, v129
	v_mul_u32_u24_e32 v167, 0xd0, v229
	v_lshl_add_u32 v167, v230, 4, v167
	v_add_u32_e32 v167, 0x10000, v167
	v_bfe_u32 v131, v175, 2, 3
	v_lshl_add_u32 v131, s14, 3, v131
	v_lshlrev_b32_e32 v131, 12, v131
	v_lshlrev_b32_e32 v174, 2, v228
	v_and_or_b32 v174, v175, 3, v174
	v_lshl_add_u32 v131, v174, 4, v131
	v_add_u32_e32 v131, 0x80, v131
	s_lshl_b32 s40, s14, 11
	s_add_i32 s41, s14, 0
	s_lshl_b32 s16, s41, 6
	s_lshl_b32 s41, s41, 10
	v_add_u32_e32 v229, s16, v175
	v_mul_u32_u24_e32 v230, 0x13b2, v229
	v_lshrrev_b32_e32 v230, 16, v230
	v_mul_u32_u24_e32 v174, 13, v230
	v_sub_u32_e32 v229, v229, v174
	v_lshlrev_b32_e32 v249, 12, v230
	v_lshl_add_u32 v249, v229, 4, v249
	v_lshlrev_b32_e32 v174, 6, v230
	v_lshl_add_u32 v174, v229, 4, v174
	v_subrev_u32_e32 v174, 0x80, v174
	v_cmp_eq_u32_e32 vcc, 12, v229
	s_nop 1
	v_cndmask_b32_e64 v249, v249, 0, vcc
	v_cmp_lt_u32_e32 vcc, 7, v229
	s_mov_b64 s[44:45], vcc
	v_cmp_gt_u32_e32 vcc, 12, v229
	s_and_b64 s[44:45], s[44:45], vcc
	s_nop 1
	v_cndmask_b32_e64 v249, v249, v174, s[44:45]
	v_mov_b32_e32 v248, 0x40000
	v_mov_b32_e32 v174, 0x1000
	v_cndmask_b32_e64 v248, v248, v174, s[44:45]
	s_add_i32 s30, s14, 8
	s_lshl_b32 s16, s30, 6
	s_lshl_b32 s30, s30, 10
	v_add_u32_e32 v229, s16, v175
	v_mul_u32_u24_e32 v230, 0x13b2, v229
	v_lshrrev_b32_e32 v230, 16, v230
	v_mul_u32_u24_e32 v174, 13, v230
	v_sub_u32_e32 v229, v229, v174
	v_lshlrev_b32_e32 v253, 12, v230
	v_lshl_add_u32 v253, v229, 4, v253
	v_lshlrev_b32_e32 v174, 6, v230
	v_lshl_add_u32 v174, v229, 4, v174
	v_subrev_u32_e32 v174, 0x80, v174
	v_cmp_eq_u32_e32 vcc, 12, v229
	s_nop 1
	v_cndmask_b32_e64 v253, v253, 0, vcc
	v_cmp_lt_u32_e32 vcc, 7, v229
	s_mov_b64 s[46:47], vcc
	v_cmp_gt_u32_e32 vcc, 12, v229
	s_and_b64 s[46:47], s[46:47], vcc
	s_nop 1
	v_cndmask_b32_e64 v253, v253, v174, s[46:47]
	v_mov_b32_e32 v252, 0x40000
	v_mov_b32_e32 v174, 0x1000
	v_cndmask_b32_e64 v252, v252, v174, s[46:47]
	v_and_b32_e32 v174, 3, v178
	v_bfe_u32 v229, v178, 2, 6
	v_lshlrev_b32_e32 v130, 4, v174
	v_lshl_or_b32 v130, v229, 6, v130
	v_mul_u32_u24_e32 v169, 0xd0, v229
	v_lshl_add_u32 v169, v174, 4, v169
	v_add_u32_e32 v169, 0x10080, v169
	v_mul_u32_u24_e32 v170, 0xd0, v183
	v_lshl_add_u32 v170, v228, 4, v170
	v_add_u32_e32 v170, 0x10000, v170
	v_and_b32_e32 v174, 3, v175
	v_lshlrev_b32_e32 v174, 3, v174
	v_mov_b32_e32 v171, v174
	v_bfe_u32 v174, v175, 2, 2
	v_lshl_or_b32 v171, v174, 6, v171
	v_bfe_u32 v174, v175, 4, 1
	v_lshl_or_b32 v171, v174, 5, v171
	v_lshl_or_b32 v171, v228, 8, v171
	s_lshl_b32 s16, s14, 5
	v_add_u32_e32 v174, s16, v183
	v_mul_u32_u24_e32 v234, 0xc00, v174
	v_lshl_add_u32 v234, v228, 4, v234
	v_lshlrev_b32_e32 v235, 2, v228
	v_add_u32_e32 v235, s16, v235
	v_lshlrev_b32_e32 v235, 11, v235
	v_lshl_add_u32 v235, v183, 1, v235
	s_lshl_b32 s17, s14, 8
	s_add_i32 s17, s17, 0x1d000
	v_lshl_add_u32 v244, v183, 2, s17
	v_lshl_add_u32 v245, v228, 4, s17
	s_add_u32 s34, s86, 0x3d796000
	s_addc_u32 s35, s87, 0
	s_lshr_b32 s12, s3, 3
	s_mov_b32 s19, s12
	s_lshr_b32 s16, s19, 5
	s_lshl_b32 s16, s16, 3
	s_add_i32 s16, s16, s43
	s_lshr_b32 s22, s16, 4
	s_and_b32 s21, s16, 15
	s_mul_i32 s17, s22, 0x2100000
	s_lshl_b32 s18, s21, 8
	s_add_i32 s17, s17, s18
	s_add_u32 s17, s17, 0x29400000
	s_mov_b32 s0, s17
	s_add_u32 s4, s86, s17
	s_addc_u32 s5, s87, 0
	s_mul_i32 s17, s22, 0x84000
	s_add_u32 s17, s17, 0x1de80000
	s_mov_b32 s1, s17
	s_add_u32 s6, s86, s17
	s_addc_u32 s7, s87, 0
	s_mov_b64 s[36:37], s[4:5]
	v_mov_b32_e32 v230, s1
	v_mov_b32_e32 v246, s0
	v_cndmask_b32_e64 v246, v246, v230, s[44:45]
	v_add_u32_e32 v246, v249, v246
	v_mov_b32_e32 v250, s0
	v_cndmask_b32_e64 v250, v250, v230, s[46:47]
	v_add_u32_e32 v250, v253, v250
	s_add_i32 m0, s41, 0x10000
	s_cmp_lt_u32 s14, 5
	global_load_lds_dwordx4 v246, s[86:87]
	v_add_u32_e32 v246, v248, v246
	s_cbranch_scc0 .Lat_kd1
	s_add_i32 m0, s30, 0x10000
	s_nop 0
	global_load_lds_dwordx4 v250, s[86:87]

; __device__ __forceinline__ unsigned cvtpk(float lo, float hi) { f32x2 v = {lo, hi}; bf16x2_t b = __builtin_convertvector(v, bf16x2_t); return *(unsigned*)&b; }
; __device__ __forceinline__ float lo16(unsigned w) { return __uint_as_float(w << 16); }
; __device__ __forceinline__ float hi16(unsigned w) { return __uint_as_float(w & 0xffff0000u); }
; __device__ void phase_attn(const Params& p, char* lds) {
;     ...
;     float m_reg = 0.f, l_reg = 0.f;
;     f32x16 o[2];
; #pragma unroll
;     for (int dd = 0; dd < 2; ++dd)
; #pragma unroll
;       for (int r = 0; r < 16; ++r) o[dd][r] = 0.f;
;     bf16x8 qr[6];
;     {
;       const bf16_t* Qw = Qg + qrow * 1536 + h * 96 + hi * 8;
; #pragma unroll
;       for (int d0 = 0; d0 < 6; ++d0) qr[d0] = *(const bf16x8*)(Qw + d0 * 16);
;       const int t = qblk * 256 + wid * 32 + r32;
;       const f32x2* tb = rope + (hi ? (t & 63) : (t >> 6)) * 8;
;       const u32x4 x1 = *(const u32x4*)&qr[4], x2 = *(const u32x4*)&qr[5];
;       u32x4 n1, n2;
; #pragma unroll
;       for (int q = 0; q < 4; ++q) {
;         const f32x2 csA = tb[2 * q], csB = tb[2 * q + 1];
;         const float a0 = lo16(x1[q]), a1 = hi16(x1[q]), b0 = lo16(x2[q]), b1 = hi16(x2[q]);
;         n1[q] = cvtpk(a0 * csA[0] - b0 * csA[1], a1 * csB[0] - b1 * csB[1]);
;         n2[q] = cvtpk(a0 * csA[1] + b0 * csA[0], a1 * csB[1] + b1 * csB[0]);
;       }
;       qr[4] = *(bf16x8*)&n1; qr[5] = *(bf16x8*)&n2;
;     }
.Lat_item:
	s_lshr_b32 s16, s12, 5
	s_lshl_b32 s16, s16, 3
	s_add_i32 s16, s16, s43
	s_and_b32 s20, s12, 31
	s_lshr_b32 s22, s16, 4
	s_and_b32 s21, s16, 15
	s_mul_i32 s17, s22, 0x2100
	s_lshl_b32 s18, s20, 8
	s_add_i32 s17, s17, s18
	s_mul_i32 s18, s17, 0xc00
	s_mul_i32 s19, s21, 0xc0
	s_add_i32 s18, s18, s19
	s_add_u32 s18, s18, 0x8400000
	s_add_u32 s10, s86, s18
	s_addc_u32 s11, s87, 0
	s_lshl_b32 s18, s17, 11
	s_lshl_b32 s19, s21, 7
	s_add_i32 s18, s18, s19
	s_add_u32 s18, s18, 0x21000000
	s_add_u32 s28, s86, s18
	s_addc_u32 s29, s87, 0
	global_load_dwordx4 v[80:83], v234, s[10:11] offset:0
	global_load_dwordx4 v[84:87], v234, s[10:11] offset:32
	global_load_dwordx4 v[88:91], v234, s[10:11] offset:64
	global_load_dwordx4 v[92:95], v234, s[10:11] offset:96
	global_load_dwordx4 v[96:99], v234, s[10:11] offset:128
	global_load_dwordx4 v[100:103], v234, s[10:11] offset:160
	s_and_b32 s16, s14, 1
	s_lshl_b32 s16, s16, 5
	v_and_b32_e32 v183, 31, v178
	v_add_u32_e32 v183, s16, v183
	v_lshlrev_b32_e32 v183, 6, v183
	s_lshl_b32 s16, s20, 2
	s_lshr_b32 s17, s14, 1
	s_add_i32 s16, s16, s17
	s_lshl_b32 s16, s16, 6
	v_mov_b32_e32 v228, s16
	v_and_b32_e32 v229, 32, v178
	v_cmp_ne_u32_e32 vcc, 0, v229
	s_nop 1
	v_cndmask_b32_e32 v183, v228, v183, vcc
	global_load_dwordx4 v[32:35], v183, s[34:35] offset:0
	global_load_dwordx4 v[36:39], v183, s[34:35] offset:16
	global_load_dwordx4 v[40:43], v183, s[34:35] offset:32
	global_load_dwordx4 v[44:47], v183, s[34:35] offset:48
	s_barrier
	s_waitcnt vmcnt(0)
	v_lshlrev_b32_e32 v175, 16, v96
	v_and_b32_e32 v183, 0xffff0000, v96
	v_lshlrev_b32_e32 v228, 16, v100
	v_and_b32_e32 v229, 0xffff0000, v100
	v_mul_f32_e32 v230, v228, v33
	v_mul_f32_e32 v174, v229, v35
	v_fma_f32 v230, v175, v32, -v230
	v_fma_f32 v174, v183, v34, -v174
	v_mul_f32_e32 v175, v175, v33
	v_mul_f32_e32 v183, v183, v35
	v_fma_f32 v175, v228, v32, v175
	v_fma_f32 v183, v229, v34, v183
	v_cvt_pk_bf16_f32 v96, v230, v174
	v_cvt_pk_bf16_f32 v100, v175, v183
	v_lshlrev_b32_e32 v175, 16, v97
	v_and_b32_e32 v183, 0xffff0000, v97
	v_lshlrev_b32_e32 v228, 16, v101
	v_and_b32_e32 v229, 0xffff0000, v101
	v_mul_f32_e32 v230, v228, v37
	v_mul_f32_e32 v174, v229, v39
	v_fma_f32 v230, v175, v36, -v230
	v_fma_f32 v174, v183, v38, -v174
	v_mul_f32_e32 v175, v175, v37
	v_mul_f32_e32 v183, v183, v39
	v_fma_f32 v175, v228, v36, v175
	v_fma_f32 v183, v229, v38, v183
	v_cvt_pk_bf16_f32 v97, v230, v174
	v_cvt_pk_bf16_f32 v101, v175, v183
	v_lshlrev_b32_e32 v175, 16, v98
	v_and_b32_e32 v183, 0xffff0000, v98
	v_lshlrev_b32_e32 v228, 16, v102
	v_and_b32_e32 v229, 0xffff0000, v102
	v_mul_f32_e32 v230, v228, v41
	v_mul_f32_e32 v174, v229, v43
	v_fma_f32 v230, v175, v40, -v230
	v_fma_f32 v174, v183, v42, -v174
	v_mul_f32_e32 v175, v175, v41
	v_mul_f32_e32 v183, v183, v43
	v_fma_f32 v175, v228, v40, v175
	v_fma_f32 v183, v229, v42, v183
	v_cvt_pk_bf16_f32 v98, v230, v174
	v_cvt_pk_bf16_f32 v102, v175, v183
	v_lshlrev_b32_e32 v175, 16, v99
	v_and_b32_e32 v183, 0xffff0000, v99
	v_lshlrev_b32_e32 v228, 16, v103
	v_and_b32_e32 v229, 0xffff0000, v103
	v_mul_f32_e32 v230, v228, v45
	v_mul_f32_e32 v174, v229, v47
	v_fma_f32 v230, v175, v44, -v230
	v_fma_f32 v174, v183, v46, -v174
	v_mul_f32_e32 v175, v175, v45
	v_mul_f32_e32 v183, v183, v47
	v_fma_f32 v175, v228, v44, v175
	v_fma_f32 v183, v229, v46, v183
	v_cvt_pk_bf16_f32 v99, v230, v174
	v_cvt_pk_bf16_f32 v103, v175, v183
	v_mov_b32_e32 v0, 0
	v_mov_b32_e32 v1, 0
	v_mov_b32_e32 v2, 0
	v_mov_b32_e32 v3, 0
	v_mov_b32_e32 v4, 0
	v_mov_b32_e32 v5, 0
	v_mov_b32_e32 v6, 0
	v_mov_b32_e32 v7, 0
	v_mov_b32_e32 v8, 0
	v_mov_b32_e32 v9, 0
	v_mov_b32_e32 v10, 0
	v_mov_b32_e32 v11, 0
	v_mov_b32_e32 v12, 0
	v_mov_b32_e32 v13, 0
	v_mov_b32_e32 v14, 0
	v_mov_b32_e32 v15, 0
	v_mov_b32_e32 v16, 0
	v_mov_b32_e32 v17, 0
	v_mov_b32_e32 v18, 0
	v_mov_b32_e32 v19, 0
	v_mov_b32_e32 v20, 0
	v_mov_b32_e32 v21, 0
	v_mov_b32_e32 v22, 0
	v_mov_b32_e32 v23, 0
	v_mov_b32_e32 v24, 0
	v_mov_b32_e32 v25, 0
	v_mov_b32_e32 v26, 0
	v_mov_b32_e32 v27, 0
	v_mov_b32_e32 v28, 0
	v_mov_b32_e32 v29, 0
	v_mov_b32_e32 v30, 0
	v_mov_b32_e32 v31, 0
	v_mov_b32_e32 v173, 0
	s_barrier
	ds_read_b128 v[184:187], v170 offset:0
	ds_read_b128 v[188:191], v170 offset:6656
	ds_read_b128 v[192:195], v170 offset:32
	ds_read_b128 v[196:199], v170 offset:6688
	s_cmp_eq_u32 s15, 0
	s_cbranch_scc1 .Lat_nostag
	s_barrier

; #define SBAR() __builtin_amdgcn_sched_barrier(0)
; #define SLOAD(i, k0) do { sr_[i].vs = *(const bf16x8*)(Kh + (size_t)((k0) + skey) * 2048 + 64 + sc8); \
;     sr_[i].ks = *(const bf16x8*)(Kh + (size_t)((k0) + skey) * 2048 + sc8); \
;     sr_[i].ps = *(const bf16x8*)(Kp + (size_t)((k0) + pkey) * 32 + pc8); } while (0)
; #define SWRITE(bb, i) do { *(bf16x8*)(V_lds + (bb) * AT_SHMV + vst) = sr_[i].vs; \
;     *(bf16x8*)(K_lds + (bb) * AT_SHMK + kst) = sr_[i].ks; \
;     *(bf16x8*)(K_lds + (bb) * AT_SHMK + pst) = sr_[i].ps; } while (0)
; #define SWAIT() asm volatile("s_waitcnt vmcnt(3)" ::: "memory")
; #define RESC(a) do { if (__any((a) < 1.f)) { if (hi == 0) al_l[r32] = (a); asm volatile("s_waitcnt lgkmcnt(0)" ::: "memory"); \
;     _Pragma("unroll") for (int dd = 0; dd < 2; ++dd) _Pragma("unroll") for (int r = 0; r < 16; ++r) o[dd][r] *= al_l[crow(r, hi)]; } } while (0)
; __device__ void phase_attn(const Params& p, char* lds) {
;     ...
;   for (int it = slot; it < nitems / 8; it += per) {
;     const int pair = (it >> 5) * 8 + xcd, qblk = it & 31;
;     const int b = pair >> 4, h = pair & 15;
;     const size_t row0 = (size_t)b * TL;
;     const size_t qrow = row0 + qblk * 256 + wid * 32 + r32;
;     const bf16_t* Kh = KVg + row0 * 2048 + h * 128;
;     const bf16_t* Kp = KPg + row0 * 32;
;     ...
;       SBAR(); at_qkt(pA0, pA1, K_lds, qr, r32, hi, -m_reg);
;       at_finishSM(pB0, pB1, alB, l_reg, pa0, pa1, pa2, pa3); SBAR();
;       if (j + 3 < NT) SLOAD(0, (j + 3) * 64); SBAR();
;       pv_d0(o, vb0 + AT_SHMV, pa0, pa1, pa2, pa3); at_partialSM(pA0, pA1, m_reg, alA, false);
;       __syncthreads(); SWAIT(); SWRITE(1, 1);
;       RESC(alA); __syncthreads();
;     }
;     SBAR(); at_qkt(pB0, pB1, K_lds + AT_SHMK, qr, r32, hi, -m_reg);
;     at_finishSM(pA0, pA1, alA, l_reg, pa0, pa1, pa2, pa3); SBAR();
;     pv_d0(o, vb0, pa0, pa1, pa2, pa3); at_partialSM(pB0, pB1, m_reg, alB, false);
;     __syncthreads(); RESC(alB);
;     at_finishSM(pB0, pB1, alB, l_reg, pa0, pa1, pa2, pa3); SBAR();
;     pv_d0(o, vb0 + AT_SHMV, pa0, pa1, pa2, pa3);
.Lat_rare3_back:
	v_add_f32_e32 v173, v173, v175
	v_cvt_pk_bf16_f32 v104, v32, v33
	v_cvt_pk_bf16_f32 v105, v34, v35
	v_cvt_pk_bf16_f32 v106, v36, v37
	v_cvt_pk_bf16_f32 v107, v38, v39
	v_cvt_pk_bf16_f32 v108, v40, v41
	v_cvt_pk_bf16_f32 v109, v42, v43
	v_cvt_pk_bf16_f32 v110, v44, v45
	v_cvt_pk_bf16_f32 v111, v46, v47
	v_cvt_pk_bf16_f32 v112, v48, v49
	v_cvt_pk_bf16_f32 v113, v50, v51
	v_cvt_pk_bf16_f32 v114, v52, v53
	v_cvt_pk_bf16_f32 v115, v54, v55
	v_cvt_pk_bf16_f32 v116, v56, v57
	v_cvt_pk_bf16_f32 v117, v58, v59
	v_cvt_pk_bf16_f32 v118, v60, v61
	v_cvt_pk_bf16_f32 v119, v62, v63
	ds_read_b128 v[184:187], v170 offset:13312
	ds_read_b128 v[188:191], v170 offset:19968
	ds_read_b128 v[192:195], v170 offset:13344
	ds_read_b128 v[196:199], v170 offset:20000
	s_barrier
	s_sub_u32 s13, s13, 1
	s_cmp_lg_u32 s13, 0
	s_cbranch_scc1 .Lat_loop
	ds_read_b128 v[200:203], v170 offset:13376
	ds_read_b128 v[204:207], v170 offset:20032
	s_waitcnt lgkmcnt(4)
	v_mfma_f32_32x32x16_bf16 v[32:47], v[184:187], v[80:83], v[64:79]
	v_mfma_f32_32x32x16_bf16 v[48:63], v[188:191], v[80:83], v[64:79]
	ds_read_b128 v[208:211], v170 offset:13408
	ds_read_b128 v[212:215], v170 offset:20064
	s_waitcnt lgkmcnt(4)
	v_mfma_f32_32x32x16_bf16 v[32:47], v[192:195], v[84:87], v[32:47]
	v_mfma_f32_32x32x16_bf16 v[48:63], v[196:199], v[84:87], v[48:63]
	ds_read_b128 v[184:187], v170 offset:13440
	ds_read_b128 v[188:191], v170 offset:20096
	s_waitcnt lgkmcnt(4)
	v_mfma_f32_32x32x16_bf16 v[32:47], v[200:203], v[88:91], v[32:47]
	v_mfma_f32_32x32x16_bf16 v[48:63], v[204:207], v[88:91], v[48:63]
	ds_read_b128 v[192:195], v170 offset:13472
	ds_read_b128 v[196:199], v170 offset:20128
	s_waitcnt lgkmcnt(4)
	v_mfma_f32_32x32x16_bf16 v[32:47], v[208:211], v[92:95], v[32:47]
	v_mfma_f32_32x32x16_bf16 v[48:63], v[212:215], v[92:95], v[48:63]
	ds_read_b64_tr_b16 v[148:149], v171 offset:0
	ds_read_b64_tr_b16 v[150:151], v171 offset:2048
	ds_read_b64_tr_b16 v[152:153], v171 offset:4096
	ds_read_b64_tr_b16 v[154:155], v171 offset:6144
	s_waitcnt lgkmcnt(6)
	v_mfma_f32_32x32x16_bf16 v[32:47], v[184:187], v[96:99], v[32:47]
	v_mfma_f32_32x32x16_bf16 v[48:63], v[188:191], v[96:99], v[48:63]
	ds_read_b64_tr_b16 v[156:157], v171 offset:8192
	ds_read_b64_tr_b16 v[158:159], v171 offset:10240
	ds_read_b64_tr_b16 v[216:217], v171 offset:12288
	ds_read_b64_tr_b16 v[218:219], v171 offset:14336
	s_waitcnt lgkmcnt(8)
	v_mfma_f32_32x32x16_bf16 v[32:47], v[192:195], v[100:103], v[32:47]
	v_mfma_f32_32x32x16_bf16 v[48:63], v[196:199], v[100:103], v[48:63]
	ds_read_b64_tr_b16 v[220:221], v171 offset:512
	ds_read_b64_tr_b16 v[222:223], v171 offset:2560
	ds_read_b64_tr_b16 v[224:225], v171 offset:4608
	ds_read_b64_tr_b16 v[226:227], v171 offset:6656
	s_waitcnt lgkmcnt(10)
	v_mfma_f32_32x32x16_bf16 v[0:15], v[104:107], v[148:151], v[0:15]
	s_waitcnt lgkmcnt(8)
	v_mfma_f32_32x32x16_bf16 v[0:15], v[108:111], v[152:155], v[0:15]
	ds_read_b64_tr_b16 v[236:237], v171 offset:8704
	ds_read_b64_tr_b16 v[238:239], v171 offset:10752
	ds_read_b64_tr_b16 v[240:241], v171 offset:12800
	ds_read_b64_tr_b16 v[242:243], v171 offset:14848
	s_waitcnt lgkmcnt(10)
	v_mfma_f32_32x32x16_bf16 v[0:15], v[112:115], v[156:159], v[0:15]
	s_waitcnt lgkmcnt(8)
	v_mfma_f32_32x32x16_bf16 v[0:15], v[116:119], v[216:219], v[0:15]
	s_waitcnt lgkmcnt(6)
	v_mfma_f32_32x32x16_bf16 v[16:31], v[104:107], v[220:223], v[16:31]
	s_waitcnt lgkmcnt(4)
	v_mfma_f32_32x32x16_bf16 v[16:31], v[108:111], v[224:227], v[16:31]
	s_waitcnt lgkmcnt(2)
	v_mfma_f32_32x32x16_bf16 v[16:31], v[112:115], v[236:239], v[16:31]
	s_waitcnt lgkmcnt(0)
	v_mfma_f32_32x32x16_bf16 v[16:31], v[116:119], v[240:243], v[16:31]
	s_barrier
	s_add_i32 s19, s12, s33
	s_lshr_b32 s16, s19, 5
	s_lshl_b32 s16, s16, 3
	s_add_i32 s16, s16, s43
	s_lshr_b32 s22, s16, 4
	s_and_b32 s21, s16, 15
	s_mul_i32 s17, s22, 0x2100000
	s_lshl_b32 s18, s21, 8
	s_add_i32 s17, s17, s18
	s_add_u32 s17, s17, 0x29400000
	s_mov_b32 s0, s17
	s_add_u32 s4, s86, s17
	s_addc_u32 s5, s87, 0
	s_mul_i32 s17, s22, 0x84000
	s_add_u32 s17, s17, 0x1de80000
	s_mov_b32 s1, s17
	s_add_u32 s6, s86, s17
	s_addc_u32 s7, s87, 0
	v_mov_b32_e32 v230, s1
	v_mov_b32_e32 v246, s0
	v_cndmask_b32_e64 v246, v246, v230, s[44:45]
	v_add_u32_e32 v246, v249, v246
	v_mov_b32_e32 v250, s0
	v_cndmask_b32_e64 v250, v250, v230, s[46:47]
	v_add_u32_e32 v250, v253, v250
	s_waitcnt vmcnt(0)
	s_add_i32 m0, s41, 0x10000
	s_cmp_lt_u32 s14, 5
	global_load_lds_dwordx4 v246, s[86:87]
	v_add_u32_e32 v246, v248, v246
	s_cbranch_scc0 .Lat_kd9
	s_add_i32 m0, s30, 0x10000
	s_nop 0
	global_load_lds_dwordx4 v250, s[86:87]

; #define SBAR() __builtin_amdgcn_sched_barrier(0)
; #define SLOAD(i, k0) do { sr_[i].vs = *(const bf16x8*)(Kh + (size_t)((k0) + skey) * 2048 + 64 + sc8); \
;     sr_[i].ks = *(const bf16x8*)(Kh + (size_t)((k0) + skey) * 2048 + sc8); \
;     sr_[i].ps = *(const bf16x8*)(Kp + (size_t)((k0) + pkey) * 32 + pc8); } while (0)
; #define SWRITE(bb, i) do { *(bf16x8*)(V_lds + (bb) * AT_SHMV + vst) = sr_[i].vs; \
;     *(bf16x8*)(K_lds + (bb) * AT_SHMK + kst) = sr_[i].ks; \
;     *(bf16x8*)(K_lds + (bb) * AT_SHMK + pst) = sr_[i].ps; } while (0)
; #define SWAIT() asm volatile("s_waitcnt vmcnt(3)" ::: "memory")
; #define RESC(a) do { if (__any((a) < 1.f)) { if (hi == 0) al_l[r32] = (a); asm volatile("s_waitcnt lgkmcnt(0)" ::: "memory"); \
;     _Pragma("unroll") for (int dd = 0; dd < 2; ++dd) _Pragma("unroll") for (int r = 0; r < 16; ++r) o[dd][r] *= al_l[crow(r, hi)]; } } while (0)
; __device__ void phase_attn(const Params& p, char* lds) {
;     ...
;       SBAR(); at_qkt(pA0, pA1, K_lds, qr, r32, hi, -m_reg);
;       at_finishSM(pB0, pB1, alB, l_reg, pa0, pa1, pa2, pa3); SBAR();
;       if (j + 3 < NT) SLOAD(0, (j + 3) * 64); SBAR();
;       pv_d0(o, vb0 + AT_SHMV, pa0, pa1, pa2, pa3); at_partialSM(pA0, pA1, m_reg, alA, false);
;       __syncthreads(); SWAIT(); SWRITE(1, 1);
;       RESC(alA); __syncthreads();
;     }
;     SBAR(); at_qkt(pB0, pB1, K_lds + AT_SHMK, qr, r32, hi, -m_reg);
;     at_finishSM(pA0, pA1, alA, l_reg, pa0, pa1, pa2, pa3); SBAR();
;     pv_d0(o, vb0, pa0, pa1, pa2, pa3); at_partialSM(pB0, pB1, m_reg, alB, false);
;     __syncthreads(); RESC(alB);
;     at_finishSM(pB0, pB1, alB, l_reg, pa0, pa1, pa2, pa3); SBAR();
;     pv_d0(o, vb0 + AT_SHMV, pa0, pa1, pa2, pa3);
.Lat_rare_t129_back:
	v_add_f32_e32 v173, v173, v175
	v_cvt_pk_bf16_f32 v104, v32, v33
	v_cvt_pk_bf16_f32 v105, v34, v35
	v_cvt_pk_bf16_f32 v106, v36, v37
	v_cvt_pk_bf16_f32 v107, v38, v39
	v_cvt_pk_bf16_f32 v108, v40, v41
	v_cvt_pk_bf16_f32 v109, v42, v43
	v_cvt_pk_bf16_f32 v110, v44, v45
	v_cvt_pk_bf16_f32 v111, v46, v47
	v_cvt_pk_bf16_f32 v112, v48, v49
	v_cvt_pk_bf16_f32 v113, v50, v51
	v_cvt_pk_bf16_f32 v114, v52, v53
	v_cvt_pk_bf16_f32 v115, v54, v55
	v_cvt_pk_bf16_f32 v116, v56, v57
	v_cvt_pk_bf16_f32 v117, v58, v59
	v_cvt_pk_bf16_f32 v118, v60, v61
	v_cvt_pk_bf16_f32 v119, v62, v63
	ds_read_b128 v[184:187], v170 offset:26624
	ds_read_b128 v[188:191], v170 offset:33280
	ds_read_b128 v[192:195], v170 offset:26656
	ds_read_b128 v[196:199], v170 offset:33312
	s_barrier
	ds_read_b128 v[200:203], v170 offset:26688
	ds_read_b128 v[204:207], v170 offset:33344
	s_waitcnt lgkmcnt(4)
	v_mfma_f32_32x32x16_bf16 v[32:47], v[184:187], v[80:83], v[64:79]
	v_mfma_f32_32x32x16_bf16 v[48:63], v[188:191], v[80:83], v[64:79]
	ds_read_b128 v[208:211], v170 offset:26720
	ds_read_b128 v[212:215], v170 offset:33376
	s_waitcnt lgkmcnt(4)
	v_mfma_f32_32x32x16_bf16 v[32:47], v[192:195], v[84:87], v[32:47]
	v_mfma_f32_32x32x16_bf16 v[48:63], v[196:199], v[84:87], v[48:63]
	ds_read_b128 v[184:187], v170 offset:26752
	ds_read_b128 v[188:191], v170 offset:33408
	s_waitcnt lgkmcnt(4)
	v_mfma_f32_32x32x16_bf16 v[32:47], v[200:203], v[88:91], v[32:47]
	v_mfma_f32_32x32x16_bf16 v[48:63], v[204:207], v[88:91], v[48:63]
	ds_read_b128 v[192:195], v170 offset:26784
	ds_read_b128 v[196:199], v170 offset:33440
	s_waitcnt lgkmcnt(4)
	v_mfma_f32_32x32x16_bf16 v[32:47], v[208:211], v[92:95], v[32:47]
	v_mfma_f32_32x32x16_bf16 v[48:63], v[212:215], v[92:95], v[48:63]
	ds_read_b64_tr_b16 v[148:149], v171 offset:16384
	ds_read_b64_tr_b16 v[150:151], v171 offset:18432
	ds_read_b64_tr_b16 v[152:153], v171 offset:20480
	ds_read_b64_tr_b16 v[154:155], v171 offset:22528
	s_waitcnt lgkmcnt(6)
	v_mfma_f32_32x32x16_bf16 v[32:47], v[184:187], v[96:99], v[32:47]
	v_mfma_f32_32x32x16_bf16 v[48:63], v[188:191], v[96:99], v[48:63]
	ds_read_b64_tr_b16 v[156:157], v171 offset:24576
	ds_read_b64_tr_b16 v[158:159], v171 offset:26624
	ds_read_b64_tr_b16 v[216:217], v171 offset:28672
	ds_read_b64_tr_b16 v[218:219], v171 offset:30720
	s_waitcnt lgkmcnt(8)
	v_mfma_f32_32x32x16_bf16 v[32:47], v[192:195], v[100:103], v[32:47]
	v_mfma_f32_32x32x16_bf16 v[48:63], v[196:199], v[100:103], v[48:63]
	ds_read_b64_tr_b16 v[220:221], v171 offset:16896
	ds_read_b64_tr_b16 v[222:223], v171 offset:18944
	ds_read_b64_tr_b16 v[224:225], v171 offset:20992
	ds_read_b64_tr_b16 v[226:227], v171 offset:23040
	s_waitcnt lgkmcnt(10)
	v_mfma_f32_32x32x16_bf16 v[0:15], v[104:107], v[148:151], v[0:15]
	s_waitcnt lgkmcnt(8)
	v_mfma_f32_32x32x16_bf16 v[0:15], v[108:111], v[152:155], v[0:15]
	ds_read_b64_tr_b16 v[236:237], v171 offset:25088
	ds_read_b64_tr_b16 v[238:239], v171 offset:27136
	ds_read_b64_tr_b16 v[240:241], v171 offset:29184
	ds_read_b64_tr_b16 v[242:243], v171 offset:31232
	s_waitcnt lgkmcnt(10)
	v_mfma_f32_32x32x16_bf16 v[0:15], v[112:115], v[156:159], v[0:15]
	s_waitcnt lgkmcnt(8)
	v_mfma_f32_32x32x16_bf16 v[0:15], v[116:119], v[216:219], v[0:15]
	s_waitcnt lgkmcnt(6)
	v_mfma_f32_32x32x16_bf16 v[16:31], v[104:107], v[220:223], v[16:31]
	s_waitcnt lgkmcnt(4)
	v_mfma_f32_32x32x16_bf16 v[16:31], v[108:111], v[224:227], v[16:31]
	s_waitcnt lgkmcnt(2)
	v_mfma_f32_32x32x16_bf16 v[16:31], v[112:115], v[236:239], v[16:31]
	s_waitcnt lgkmcnt(0)
	v_mfma_f32_32x32x16_bf16 v[16:31], v[116:119], v[240:243], v[16:31]
	s_barrier
	s_mov_b64 s[36:37], s[4:5]
	s_waitcnt vmcnt(0)
	s_add_i32 m0, s41, 0x13400
	s_cmp_lt_u32 s14, 5
	global_load_lds_dwordx4 v246, s[86:87]
	v_add_u32_e32 v246, v248, v246
	s_cbranch_scc0 .Lat_kd10
	s_add_i32 m0, s30, 0x13400
	s_nop 0
	global_load_lds_dwordx4 v250, s[86:87]

; __device__ __forceinline__ int crow(int r, int hi) { return (r & 3) + 8 * (r >> 2) + 4 * hi; }
; #define SBAR() __builtin_amdgcn_sched_barrier(0)
; #define SLOAD(i, k0) do { sr_[i].vs = *(const bf16x8*)(Kh + (size_t)((k0) + skey) * 2048 + 64 + sc8); \
;     sr_[i].ks = *(const bf16x8*)(Kh + (size_t)((k0) + skey) * 2048 + sc8); \
;     sr_[i].ps = *(const bf16x8*)(Kp + (size_t)((k0) + pkey) * 32 + pc8); } while (0)
; #define SWRITE(bb, i) do { *(bf16x8*)(V_lds + (bb) * AT_SHMV + vst) = sr_[i].vs; \
;     *(bf16x8*)(K_lds + (bb) * AT_SHMK + kst) = sr_[i].ks; \
;     *(bf16x8*)(K_lds + (bb) * AT_SHMK + pst) = sr_[i].ps; } while (0)
; #define SWAIT() asm volatile("s_waitcnt vmcnt(3)" ::: "memory")
; #define RESC(a) do { if (__any((a) < 1.f)) { if (hi == 0) al_l[r32] = (a); asm volatile("s_waitcnt lgkmcnt(0)" ::: "memory"); \
;     _Pragma("unroll") for (int dd = 0; dd < 2; ++dd) _Pragma("unroll") for (int r = 0; r < 16; ++r) o[dd][r] *= al_l[crow(r, hi)]; } } while (0)
; __device__ void phase_attn(const Params& p, char* lds) {
;     ...
;       SBAR(); at_qkt(pA0, pA1, K_lds, qr, r32, hi, -m_reg);
;       at_finishSM(pB0, pB1, alB, l_reg, pa0, pa1, pa2, pa3); SBAR();
;       if (j + 3 < NT) SLOAD(0, (j + 3) * 64); SBAR();
;       pv_d0(o, vb0 + AT_SHMV, pa0, pa1, pa2, pa3); at_partialSM(pA0, pA1, m_reg, alA, false);
;       __syncthreads(); SWAIT(); SWRITE(1, 1);
;       RESC(alA); __syncthreads();
;     }
;     SBAR(); at_qkt(pB0, pB1, K_lds + AT_SHMK, qr, r32, hi, -m_reg);
;     at_finishSM(pA0, pA1, alA, l_reg, pa0, pa1, pa2, pa3); SBAR();
;     pv_d0(o, vb0, pa0, pa1, pa2, pa3); at_partialSM(pB0, pB1, m_reg, alB, false);
;     __syncthreads(); RESC(alB);
;     at_finishSM(pB0, pB1, alB, l_reg, pa0, pa1, pa2, pa3); SBAR();
;     pv_d0(o, vb0 + AT_SHMV, pa0, pa1, pa2, pa3);
;     if (hi == 0) li_l[r32] = l_reg;
;     asm volatile("s_waitcnt lgkmcnt(0)" ::: "memory");
;     float rli[16];
; #pragma unroll
;     for (int r = 0; r < 16; ++r) rli[r] = __builtin_amdgcn_rcpf(li_l[crow(r, hi)]);
;     bf16_t* Gw = G1 + (row0 + qblk * 256 + wid * 32) * 1024 + h * 64 + r32;
;     bf16_t gin[32];
; #pragma unroll
;     for (int r = 0; r < 16; ++r) { gin[2 * r] = Gw[(size_t)crow(r, hi) * 1024]; gin[2 * r + 1] = Gw[(size_t)crow(r, hi) * 1024 + 32]; }
.Lat_rare_t130_back:
	v_add_f32_e32 v173, v173, v175
	v_cvt_pk_bf16_f32 v104, v32, v33
	v_cvt_pk_bf16_f32 v105, v34, v35
	v_cvt_pk_bf16_f32 v106, v36, v37
	v_cvt_pk_bf16_f32 v107, v38, v39
	v_cvt_pk_bf16_f32 v108, v40, v41
	v_cvt_pk_bf16_f32 v109, v42, v43
	v_cvt_pk_bf16_f32 v110, v44, v45
	v_cvt_pk_bf16_f32 v111, v46, v47
	v_cvt_pk_bf16_f32 v112, v48, v49
	v_cvt_pk_bf16_f32 v113, v50, v51
	v_cvt_pk_bf16_f32 v114, v52, v53
	v_cvt_pk_bf16_f32 v115, v54, v55
	v_cvt_pk_bf16_f32 v116, v56, v57
	v_cvt_pk_bf16_f32 v117, v58, v59
	v_cvt_pk_bf16_f32 v118, v60, v61
	v_cvt_pk_bf16_f32 v119, v62, v63
	ds_read_b128 v[184:187], v170 offset:39936
	ds_read_b128 v[188:191], v170 offset:46592
	ds_read_b128 v[192:195], v170 offset:39968
	ds_read_b128 v[196:199], v170 offset:46624
	s_barrier
	ds_read_b128 v[200:203], v170 offset:40000
	ds_read_b128 v[204:207], v170 offset:46656
	s_waitcnt lgkmcnt(4)
	v_mfma_f32_32x32x16_bf16 v[32:47], v[184:187], v[80:83], v[64:79]
	v_mfma_f32_32x32x16_bf16 v[48:63], v[188:191], v[80:83], v[64:79]
	ds_read_b128 v[208:211], v170 offset:40032
	ds_read_b128 v[212:215], v170 offset:46688
	s_waitcnt lgkmcnt(4)
	v_mfma_f32_32x32x16_bf16 v[32:47], v[192:195], v[84:87], v[32:47]
	v_mfma_f32_32x32x16_bf16 v[48:63], v[196:199], v[84:87], v[48:63]
	ds_read_b128 v[184:187], v170 offset:40064
	ds_read_b128 v[188:191], v170 offset:46720
	s_waitcnt lgkmcnt(4)
	v_mfma_f32_32x32x16_bf16 v[32:47], v[200:203], v[88:91], v[32:47]
	v_mfma_f32_32x32x16_bf16 v[48:63], v[204:207], v[88:91], v[48:63]
	ds_read_b128 v[192:195], v170 offset:40096
	ds_read_b128 v[196:199], v170 offset:46752
	s_waitcnt lgkmcnt(4)
	v_mfma_f32_32x32x16_bf16 v[32:47], v[208:211], v[92:95], v[32:47]
	v_mfma_f32_32x32x16_bf16 v[48:63], v[212:215], v[92:95], v[48:63]
	ds_read_b64_tr_b16 v[148:149], v171 offset:32768
	ds_read_b64_tr_b16 v[150:151], v171 offset:34816
	ds_read_b64_tr_b16 v[152:153], v171 offset:36864
	ds_read_b64_tr_b16 v[154:155], v171 offset:38912
	s_waitcnt lgkmcnt(6)
	v_mfma_f32_32x32x16_bf16 v[32:47], v[184:187], v[96:99], v[32:47]
	v_mfma_f32_32x32x16_bf16 v[48:63], v[188:191], v[96:99], v[48:63]
	ds_read_b64_tr_b16 v[156:157], v171 offset:40960
	ds_read_b64_tr_b16 v[158:159], v171 offset:43008
	ds_read_b64_tr_b16 v[216:217], v171 offset:45056
	ds_read_b64_tr_b16 v[218:219], v171 offset:47104
	s_waitcnt lgkmcnt(8)
	v_mfma_f32_32x32x16_bf16 v[32:47], v[192:195], v[100:103], v[32:47]
	v_mfma_f32_32x32x16_bf16 v[48:63], v[196:199], v[100:103], v[48:63]
	ds_read_b64_tr_b16 v[220:221], v171 offset:33280
	ds_read_b64_tr_b16 v[222:223], v171 offset:35328
	ds_read_b64_tr_b16 v[224:225], v171 offset:37376
	ds_read_b64_tr_b16 v[226:227], v171 offset:39424
	s_waitcnt lgkmcnt(10)
	v_mfma_f32_32x32x16_bf16 v[0:15], v[104:107], v[148:151], v[0:15]
	s_waitcnt lgkmcnt(8)
	v_mfma_f32_32x32x16_bf16 v[0:15], v[108:111], v[152:155], v[0:15]
	ds_read_b64_tr_b16 v[236:237], v171 offset:41472
	ds_read_b64_tr_b16 v[238:239], v171 offset:43520
	ds_read_b64_tr_b16 v[240:241], v171 offset:45568
	ds_read_b64_tr_b16 v[242:243], v171 offset:47616
	s_waitcnt lgkmcnt(10)
	v_mfma_f32_32x32x16_bf16 v[0:15], v[112:115], v[156:159], v[0:15]
	s_waitcnt lgkmcnt(8)
	v_mfma_f32_32x32x16_bf16 v[0:15], v[116:119], v[216:219], v[0:15]
	s_waitcnt lgkmcnt(6)
	v_mfma_f32_32x32x16_bf16 v[16:31], v[104:107], v[220:223], v[16:31]
	s_waitcnt lgkmcnt(4)
	v_mfma_f32_32x32x16_bf16 v[16:31], v[108:111], v[224:227], v[16:31]
	s_waitcnt lgkmcnt(2)
	v_mfma_f32_32x32x16_bf16 v[16:31], v[112:115], v[236:239], v[16:31]
	s_waitcnt lgkmcnt(0)
	v_mfma_f32_32x32x16_bf16 v[16:31], v[116:119], v[240:243], v[16:31]
	s_barrier
	s_add_u32 s8, s28, 0x0
	s_addc_u32 s9, s29, 0
	global_load_ushort v120, v235, s[8:9] offset:0
	global_load_ushort v121, v235, s[8:9] offset:64
	global_load_ushort v122, v235, s[8:9] offset:2048
	global_load_ushort v123, v235, s[8:9] offset:2112
	s_add_u32 s8, s28, 0x1000
	s_addc_u32 s9, s29, 0
	global_load_ushort v124, v235, s[8:9] offset:0
	global_load_ushort v125, v235, s[8:9] offset:64
	global_load_ushort v126, v235, s[8:9] offset:2048
	global_load_ushort v127, v235, s[8:9] offset:2112
	s_add_u32 s8, s28, 0x4000
	s_addc_u32 s9, s29, 0
	global_load_ushort v132, v235, s[8:9] offset:0
	global_load_ushort v133, v235, s[8:9] offset:64
	global_load_ushort v134, v235, s[8:9] offset:2048
	global_load_ushort v135, v235, s[8:9] offset:2112
	s_add_u32 s8, s28, 0x5000
	s_addc_u32 s9, s29, 0
	global_load_ushort v136, v235, s[8:9] offset:0
	global_load_ushort v137, v235, s[8:9] offset:64
	global_load_ushort v138, v235, s[8:9] offset:2048
	global_load_ushort v139, v235, s[8:9] offset:2112
	s_add_u32 s8, s28, 0x8000
	s_addc_u32 s9, s29, 0
	global_load_ushort v140, v235, s[8:9] offset:0
	global_load_ushort v141, v235, s[8:9] offset:64
	global_load_ushort v142, v235, s[8:9] offset:2048
	global_load_ushort v143, v235, s[8:9] offset:2112
	s_add_u32 s8, s28, 0x9000
	s_addc_u32 s9, s29, 0
	global_load_ushort v144, v235, s[8:9] offset:0
	global_load_ushort v145, v235, s[8:9] offset:64
	global_load_ushort v146, v235, s[8:9] offset:2048
	global_load_ushort v147, v235, s[8:9] offset:2112
	s_add_u32 s8, s28, 0xc000
	s_addc_u32 s9, s29, 0
	global_load_ushort v200, v235, s[8:9] offset:0
	global_load_ushort v201, v235, s[8:9] offset:64
	global_load_ushort v202, v235, s[8:9] offset:2048
	global_load_ushort v203, v235, s[8:9] offset:2112
	s_add_u32 s8, s28, 0xd000
	s_addc_u32 s9, s29, 0
	global_load_ushort v204, v235, s[8:9] offset:0
	global_load_ushort v205, v235, s[8:9] offset:64
	global_load_ushort v206, v235, s[8:9] offset:2048
	global_load_ushort v207, v235, s[8:9] offset:2112
	s_waitcnt vmcnt(32)
	s_add_i32 m0, s41, 0x16800
	s_cmp_lt_u32 s14, 5
	global_load_lds_dwordx4 v246, s[86:87]
	v_add_u32_e32 v246, v248, v246
	s_cbranch_scc0 .Lat_kd11
	s_add_i32 m0, s30, 0x16800
	s_nop 0
	global_load_lds_dwordx4 v250, s[86:87]
; #define SBAR() __builtin_amdgcn_sched_barrier(0)
; __device__ __forceinline__ void at_partialSM(f32x16& p0, f32x16& p1, float& m_reg, float& alpha, bool force) {
;     ...
;     alpha = force ? 1.f : __builtin_amdgcn_exp2f(-dlt); m_reg += dlt;
; #pragma unroll
;     for (int r = 0; r < 16; ++r) { p0[r] -= dlt; p1[r] -= dlt; }
;   }
; #pragma unroll
;   for (int r = 0; r < 16; ++r) p0[r] = __builtin_amdgcn_exp2f(p0[r]);
; }
; __device__ __forceinline__ void at_finishSM(f32x16& p0, f32x16& p1, float alpha, float& l_reg, bf16x8& pa0, bf16x8& pa1, bf16x8& pa2, bf16x8& pa3) {
; #pragma unroll
;   for (int r = 0; r < 16; ++r) p1[r] = __builtin_amdgcn_exp2f(p1[r]);
;   float ps = 0;
; #pragma unroll
;   for (int r = 0; r < 16; ++r) ps += p0[r];
; #pragma unroll
;   for (int r = 0; r < 16; ++r) ps += p1[r];
;   { auto rr = __builtin_amdgcn_permlane32_swap(__float_as_uint(ps), __float_as_uint(ps), false, false);
;     ps = __uint_as_float(rr[0]) + __uint_as_float(rr[1]); }
;   l_reg = l_reg * alpha + ps;
; __device__ void phase_attn(const Params& p, char* lds) {
;     ...
;     at_finishSM(pB0, pB1, alB, l_reg, pa0, pa1, pa2, pa3); SBAR();
;     pv_d0(o, vb0 + AT_SHMV, pa0, pa1, pa2, pa3);
.Lat_kd11:
	v_add_u32_e32 v250, v252, v250
	s_add_i32 m0, s40, 0x4000
	s_nop 0
	global_load_lds_dwordx4 v131, s[36:37]
	s_add_u32 s36, s36, 0x40000
	s_addc_u32 s37, s37, 0
	v_exp_f32_e32 v32, v32
	v_exp_f32_e32 v48, v48
	v_exp_f32_e32 v33, v33
	v_exp_f32_e32 v49, v49
	v_exp_f32_e32 v34, v34
	v_exp_f32_e32 v50, v50
	v_exp_f32_e32 v35, v35
	v_exp_f32_e32 v51, v51
	v_exp_f32_e32 v36, v36
	v_exp_f32_e32 v52, v52
	v_exp_f32_e32 v37, v37
	v_exp_f32_e32 v53, v53
	v_exp_f32_e32 v38, v38
	v_exp_f32_e32 v54, v54
	v_exp_f32_e32 v39, v39
	v_exp_f32_e32 v55, v55
	v_exp_f32_e32 v40, v40
	v_exp_f32_e32 v56, v56
	v_exp_f32_e32 v41, v41
	v_exp_f32_e32 v57, v57
	v_exp_f32_e32 v42, v42
	v_exp_f32_e32 v58, v58
	v_exp_f32_e32 v43, v43
	v_exp_f32_e32 v59, v59
	v_exp_f32_e32 v44, v44
	v_exp_f32_e32 v60, v60
	v_exp_f32_e32 v45, v45
	v_exp_f32_e32 v61, v61
	v_exp_f32_e32 v46, v46
	v_exp_f32_e32 v62, v62
	v_exp_f32_e32 v47, v47
	v_exp_f32_e32 v63, v63
	v_add_f32_e32 v175, v32, v33
	v_add_f32_e32 v174, v48, v49
	v_add_f32_e32 v175, v175, v34
	v_add_f32_e32 v174, v174, v50
	v_add_f32_e32 v175, v175, v35
	v_add_f32_e32 v174, v174, v51
	v_add_f32_e32 v175, v175, v36
	v_add_f32_e32 v174, v174, v52
	v_add_f32_e32 v175, v175, v37
	v_add_f32_e32 v174, v174, v53
	v_add_f32_e32 v175, v175, v38
	v_add_f32_e32 v174, v174, v54
	v_add_f32_e32 v175, v175, v39
	v_add_f32_e32 v174, v174, v55
	v_add_f32_e32 v175, v175, v40
	v_add_f32_e32 v174, v174, v56
	v_add_f32_e32 v175, v175, v41
	v_add_f32_e32 v174, v174, v57
	v_add_f32_e32 v175, v175, v42
	v_add_f32_e32 v174, v174, v58
	v_add_f32_e32 v175, v175, v43
	v_add_f32_e32 v174, v174, v59
	v_add_f32_e32 v175, v175, v44
	v_add_f32_e32 v174, v174, v60
	v_add_f32_e32 v175, v175, v45
	v_add_f32_e32 v174, v174, v61
	v_add_f32_e32 v175, v175, v46
	v_add_f32_e32 v174, v174, v62
	v_add_f32_e32 v175, v175, v47
	v_add_f32_e32 v174, v174, v63
	v_add_f32_e32 v175, v175, v174
	v_cmp_ge_f32_e32 vcc, s23, v175
	s_cmp_eq_u64 vcc, exec
	s_cbranch_scc0 .Lat_rare_t131
.Lat_rare_t131_back:
	v_add_f32_e32 v173, v173, v175
	v_cvt_pk_bf16_f32 v104, v32, v33
	v_cvt_pk_bf16_f32 v105, v34, v35
	v_cvt_pk_bf16_f32 v106, v36, v37
	v_cvt_pk_bf16_f32 v107, v38, v39
	v_cvt_pk_bf16_f32 v108, v40, v41
	v_cvt_pk_bf16_f32 v109, v42, v43
	v_cvt_pk_bf16_f32 v110, v44, v45
	v_cvt_pk_bf16_f32 v111, v46, v47
	v_cvt_pk_bf16_f32 v112, v48, v49
	v_cvt_pk_bf16_f32 v113, v50, v51
	v_cvt_pk_bf16_f32 v114, v52, v53
	v_cvt_pk_bf16_f32 v115, v54, v55
	v_cvt_pk_bf16_f32 v116, v56, v57
	v_cvt_pk_bf16_f32 v117, v58, v59
	v_cvt_pk_bf16_f32 v118, v60, v61
	v_cvt_pk_bf16_f32 v119, v62, v63
	s_barrier
	ds_read_b64_tr_b16 v[148:149], v171 offset:49152
	ds_read_b64_tr_b16 v[150:151], v171 offset:51200
	ds_read_b64_tr_b16 v[152:153], v171 offset:53248
	ds_read_b64_tr_b16 v[154:155], v171 offset:55296
	ds_read_b64_tr_b16 v[156:157], v171 offset:57344
	ds_read_b64_tr_b16 v[158:159], v171 offset:59392
	ds_read_b64_tr_b16 v[216:217], v171 offset:61440
	ds_read_b64_tr_b16 v[218:219], v171 offset:63488
	ds_read_b64_tr_b16 v[220:221], v171 offset:49664
	ds_read_b64_tr_b16 v[222:223], v171 offset:51712
	ds_read_b64_tr_b16 v[224:225], v171 offset:53760
	ds_read_b64_tr_b16 v[226:227], v171 offset:55808
	s_waitcnt lgkmcnt(10)
	v_mfma_f32_32x32x16_bf16 v[0:15], v[104:107], v[148:151], v[0:15]
	s_waitcnt lgkmcnt(8)
	v_mfma_f32_32x32x16_bf16 v[0:15], v[108:111], v[152:155], v[0:15]
	ds_read_b64_tr_b16 v[236:237], v171 offset:57856
	ds_read_b64_tr_b16 v[238:239], v171 offset:59904
	ds_read_b64_tr_b16 v[240:241], v171 offset:61952
	ds_read_b64_tr_b16 v[242:243], v171 offset:64000
	s_waitcnt lgkmcnt(10)
	v_mfma_f32_32x32x16_bf16 v[0:15], v[112:115], v[156:159], v[0:15]
	s_waitcnt lgkmcnt(8)
	v_mfma_f32_32x32x16_bf16 v[0:15], v[116:119], v[216:219], v[0:15]
	s_waitcnt lgkmcnt(6)
	v_mfma_f32_32x32x16_bf16 v[16:31], v[104:107], v[220:223], v[16:31]
	s_waitcnt lgkmcnt(4)
	v_mfma_f32_32x32x16_bf16 v[16:31], v[108:111], v[224:227], v[16:31]
	s_waitcnt lgkmcnt(2)
	v_mfma_f32_32x32x16_bf16 v[16:31], v[112:115], v[236:239], v[16:31]
	s_waitcnt lgkmcnt(0)
	v_mfma_f32_32x32x16_bf16 v[16:31], v[116:119], v[240:243], v[16:31]
	s_cmp_lg_u32 s15, 0
	s_cbranch_scc1 .Lat_nobal
	s_barrier
